# streaming hint: the weight-prep transpose reads the f32 weights (read exactly once) with non-temporal loads
# baseline (speedup 1.0000x reference)
; DI void transpose_tile(const TJob& j, int tid, float* lds  ) {
;     ...
;   if (j.valid) {
;     const int n4 = (tid & 31) * 4, kb = tid >> 5;
;     f32x4 v[8];
; #pragma unroll
;     for (int i = 0; i < 8; ++i) {
;       const int kk = kb + 8 * i;
;       v[i] = (n4 < j.nvalid) ? *(const f32x4*)(j.W + (size_t)(j.k0 + kk) * j.nsrc + j.src_col0 + n4) : (f32x4){0.f, 0.f, 0.f, 0.f};
;     }
.LBB0_36:
	s_or_b64 exec, exec, s[6:7]
	s_barrier
	s_and_saveexec_b64 s[0:1], s[4:5]
	s_cbranch_execz .LBB0_62
	v_or_b32_e32 v50, v40, v34
	v_ashrrev_i32_e32 v5, 31, v4
	v_lshl_add_u64 v[2:3], v[4:5], 2, v[2:3]
	v_ashrrev_i32_e32 v51, 31, v50
	v_lshl_add_u64 v[52:53], v[2:3], 0, v[36:37]
	v_mov_b32_e32 v26, 0
	v_mul_lo_u32 v41, v48, v51
	v_mov_b32_e32 v30, 0
	v_mov_b32_e32 v31, 0
	v_mov_b32_e32 v32, 0
	v_mov_b32_e32 v33, 0
	s_and_saveexec_b64 s[6:7], s[18:19]
	s_cbranch_execz .LBB0_39
	v_mul_lo_u32 v4, v49, v50
	v_mad_u64_u32 v[2:3], s[24:25], v48, v50, 0
	v_add3_u32 v3, v3, v41, v4
	v_lshl_add_u64 v[2:3], v[2:3], 2, v[52:53]
	global_load_dwordx4 v[30:33], v[2:3], off nt
.LBB0_39:
	s_or_b64 exec, exec, s[6:7]
	v_mov_b32_e32 v27, 0
	v_mov_b32_e32 v28, 0
	v_mov_b32_e32 v29, 0
	s_and_saveexec_b64 s[6:7], s[18:19]
	s_cbranch_execz .LBB0_41
	v_or_b32_e32 v2, 8, v50
	v_mul_lo_u32 v4, v49, v2
	v_mad_u64_u32 v[2:3], s[24:25], v48, v2, 0
	v_add3_u32 v3, v3, v41, v4
	v_lshl_add_u64 v[2:3], v[2:3], 2, v[52:53]
	global_load_dwordx4 v[26:29], v[2:3], off nt
.LBB0_41:
	s_or_b64 exec, exec, s[6:7]
	v_mov_b32_e32 v14, 0
	v_mov_b32_e32 v22, 0
	v_mov_b32_e32 v23, 0
	v_mov_b32_e32 v24, 0
	v_mov_b32_e32 v25, 0
	s_and_saveexec_b64 s[6:7], s[18:19]
	s_cbranch_execz .LBB0_43
	v_or_b32_e32 v2, 16, v50
	v_mul_lo_u32 v4, v49, v2
	v_mad_u64_u32 v[2:3], s[24:25], v48, v2, 0
	v_add3_u32 v3, v3, v41, v4
	v_lshl_add_u64 v[2:3], v[2:3], 2, v[52:53]
	global_load_dwordx4 v[22:25], v[2:3], off nt
.LBB0_43:
	s_or_b64 exec, exec, s[6:7]
	v_mov_b32_e32 v15, 0
	v_mov_b32_e32 v16, 0
	v_mov_b32_e32 v17, 0
	s_and_saveexec_b64 s[6:7], s[18:19]
	s_cbranch_execz .LBB0_45
	v_or_b32_e32 v2, 24, v50
	v_mul_lo_u32 v4, v49, v2
	v_mad_u64_u32 v[2:3], s[24:25], v48, v2, 0
	v_add3_u32 v3, v3, v41, v4
	v_lshl_add_u64 v[2:3], v[2:3], 2, v[52:53]
	global_load_dwordx4 v[14:17], v[2:3], off nt
.LBB0_45:
	s_or_b64 exec, exec, s[6:7]
	v_mov_b32_e32 v6, 0
	v_mov_b32_e32 v18, 0
	v_mov_b32_e32 v19, 0
	v_mov_b32_e32 v20, 0
	v_mov_b32_e32 v21, 0
	s_and_saveexec_b64 s[6:7], s[18:19]
	s_cbranch_execz .LBB0_47
	v_or_b32_e32 v2, 32, v50
	v_mul_lo_u32 v4, v49, v2
	v_mad_u64_u32 v[2:3], s[24:25], v48, v2, 0
	v_add3_u32 v3, v3, v41, v4
	v_lshl_add_u64 v[2:3], v[2:3], 2, v[52:53]
	global_load_dwordx4 v[18:21], v[2:3], off nt
.LBB0_47:
	s_or_b64 exec, exec, s[6:7]
	v_mov_b32_e32 v7, 0
	v_mov_b32_e32 v8, 0
	v_mov_b32_e32 v9, 0
	s_and_saveexec_b64 s[6:7], s[18:19]
	s_cbranch_execz .LBB0_49
	v_or_b32_e32 v2, 40, v50
	v_mul_lo_u32 v4, v49, v2
	v_mad_u64_u32 v[2:3], s[24:25], v48, v2, 0
	v_add3_u32 v3, v3, v41, v4
	v_lshl_add_u64 v[2:3], v[2:3], 2, v[52:53]
	global_load_dwordx4 v[6:9], v[2:3], off nt
.LBB0_49:
	s_or_b64 exec, exec, s[6:7]
	v_mov_b32_e32 v2, 0
	v_mov_b32_e32 v10, 0
	v_mov_b32_e32 v11, 0
	v_mov_b32_e32 v12, 0
	v_mov_b32_e32 v13, 0
	s_and_saveexec_b64 s[6:7], s[18:19]
	s_cbranch_execz .LBB0_51
	v_or_b32_e32 v3, 48, v50
	v_mul_lo_u32 v10, v49, v3
	v_mad_u64_u32 v[4:5], s[24:25], v48, v3, 0
	v_add3_u32 v5, v5, v41, v10
	v_lshl_add_u64 v[4:5], v[4:5], 2, v[52:53]
	global_load_dwordx4 v[10:13], v[4:5], off nt
